# global prefetch issue moved to after the first six MFMAs of the block
# baseline (speedup 1.0000x reference)
.LBB0_542:
	s_cmp_gt_u32 s52, s51
	s_cbranch_scc1 .Lh1_skip
	s_mul_i32 s61, s25, 0x2200
	s_and_b32 s42, s52, 2
	s_mulk_i32 s42, 0x3400
	v_add_u32_e32 v0, s42, v160
	v_add_u32_e32 v242, s61, v161
	v_add_u32_e32 v163, 0xe000, v242
	v_add_u32_e32 v242, 0xd000, v242
	ds_read_b128 v[82:85], v0 offset:13312
	ds_read_b128 v[98:101], v0 offset:19968
	ds_read_b128 v[164:167], v0 offset:13344
	ds_read_b128 v[168:171], v0 offset:20000
	ds_read2_b64 v[238:241], v242 offset0:0 offset1:2
	ds_read2_b64 v[234:237], v163 offset0:32 offset1:34
	ds_read_b128 v[172:175], v0 offset:13376
	ds_read_b128 v[176:179], v0 offset:20032
	ds_read_b128 v[180:183], v0 offset:13408
	ds_read_b128 v[184:187], v0 offset:20064
	ds_read_b128 v[188:191], v0 offset:13440
	ds_read_b128 v[192:195], v0 offset:20096
	ds_read_b128 v[196:199], v0 offset:13472
	ds_read_b128 v[220:223], v0 offset:20128
	v_exp_f32_e32 v50, v50
	v_exp_f32_e32 v51, v51
	v_exp_f32_e32 v52, v52
	v_exp_f32_e32 v53, v53
	v_exp_f32_e32 v54, v54
	v_exp_f32_e32 v55, v55
	v_exp_f32_e32 v56, v56
	v_exp_f32_e32 v57, v57
	s_waitcnt lgkmcnt(13)
	v_mfma_f32_32x32x16_bf16 v[82:97], v[82:85], v[122:125], 0
	v_cvt_pk_bf16_f32 v224, v50, v51
	v_cvt_pk_bf16_f32 v225, v52, v53
	v_cvt_pk_bf16_f32 v226, v54, v55
	v_cvt_pk_bf16_f32 v227, v56, v57
	v_exp_f32_e32 v58, v58
	v_add_f32_e32 v200, v50, v51
	s_waitcnt lgkmcnt(12)
	v_mfma_f32_32x32x16_bf16 v[98:113], v[98:101], v[122:125], 0
	v_exp_f32_e32 v59, v59
	v_exp_f32_e32 v60, v60
	v_add_f32_e32 v201, v52, v53
	v_exp_f32_e32 v61, v61
	s_waitcnt lgkmcnt(11)
	v_mfma_f32_32x32x16_bf16 v[82:97], v[164:167], v[126:129], v[82:97]
	v_exp_f32_e32 v62, v62
	v_add_f32_e32 v200, v200, v54
	v_exp_f32_e32 v63, v63
	v_add_f32_e32 v201, v201, v55
	v_exp_f32_e32 v64, v64
	s_waitcnt lgkmcnt(10)
	v_mfma_f32_32x32x16_bf16 v[98:113], v[168:171], v[126:129], v[98:113]
	ds_read2_b64 v[164:167], v242 offset0:4 offset1:6
	ds_read2_b64 v[168:171], v163 offset0:36 offset1:38
	v_add_f32_e32 v200, v200, v56
	v_exp_f32_e32 v65, v65
	v_add_f32_e32 v201, v201, v57
	v_cvt_pk_bf16_f32 v228, v58, v59
	v_cvt_pk_bf16_f32 v229, v60, v61
	s_waitcnt lgkmcnt(11)
	v_mfma_f32_32x32x16_bf16 v[18:33], v[238:241], v[224:227], v[18:33]
	v_cvt_pk_bf16_f32 v230, v62, v63
	v_cvt_pk_bf16_f32 v231, v64, v65
	v_exp_f32_e32 v66, v66
	v_add_f32_e32 v200, v200, v58
	v_exp_f32_e32 v67, v67
	v_add_f32_e32 v201, v201, v59
	s_waitcnt lgkmcnt(10)
	v_mfma_f32_32x32x16_bf16 v[34:49], v[234:237], v[224:227], v[34:49]
	v_exp_f32_e32 v68, v68
	v_add_f32_e32 v200, v200, v60
	v_exp_f32_e32 v69, v69
	v_add_f32_e32 v201, v201, v61
	v_exp_f32_e32 v70, v70
	s_add_i32 s60, s52, 3
	s_cmp_lt_u32 s60, s48
	s_cselect_b64 s[58:59], -1, 0
	s_cmp_ge_u32 s60, s48
	s_cbranch_scc1 .Lp1a_546
	s_waitcnt vmcnt(0)
	v_lshl_add_u64 v[2:3], s[54:55], 0, v[154:155]
	v_add_co_u32_e32 v2, vcc, 0xbe09000, v2
	s_nop 1
	v_addc_co_u32_e32 v3, vcc, 0, v3, vcc
	global_load_dwordx4 v[2:5], v[2:3], off
	s_and_saveexec_b64 s[42:43], s[40:41]
	s_cbranch_execz .Lp1a_545
	v_lshl_add_u64 v[10:11], s[54:55], 0, v[152:153]
	v_add_co_u32_e32 v10, vcc, 0xbe09000, v10
	s_nop 1
	v_addc_co_u32_e32 v11, vcc, 0, v11, vcc
	global_load_dwordx4 v[10:13], v[10:11], off

.Lp1a_end:
	s_waitcnt lgkmcnt(9)
	v_mfma_f32_32x32x16_bf16 v[82:97], v[172:175], v[134:137], v[82:97]
	v_add_f32_e32 v200, v200, v62
	v_exp_f32_e32 v71, v71
	v_add_f32_e32 v201, v201, v63
	v_exp_f32_e32 v72, v72
	v_add_f32_e32 v200, v200, v64
	s_waitcnt lgkmcnt(8)
	v_mfma_f32_32x32x16_bf16 v[98:113], v[176:179], v[134:137], v[98:113]
	ds_read2_b64 v[172:175], v242 offset0:8 offset1:10
	ds_read2_b64 v[176:179], v163 offset0:40 offset1:42
	v_exp_f32_e32 v73, v73
	v_add_f32_e32 v201, v201, v65
	v_cvt_pk_bf16_f32 v224, v66, v67
	v_cvt_pk_bf16_f32 v225, v68, v69
	v_cvt_pk_bf16_f32 v226, v70, v71
	s_waitcnt lgkmcnt(3)
	v_mfma_f32_32x32x16_bf16 v[18:33], v[164:167], v[228:231], v[18:33]
	v_cvt_pk_bf16_f32 v227, v72, v73
	v_exp_f32_e32 v74, v74
	v_add_f32_e32 v200, v200, v66
	v_exp_f32_e32 v75, v75
	v_add_f32_e32 v201, v201, v67
	s_waitcnt lgkmcnt(2)
	v_mfma_f32_32x32x16_bf16 v[34:49], v[168:171], v[228:231], v[34:49]
	v_exp_f32_e32 v76, v76
	v_add_f32_e32 v200, v200, v68
	v_exp_f32_e32 v77, v77
	v_add_f32_e32 v201, v201, v69
	v_exp_f32_e32 v78, v78
	s_waitcnt lgkmcnt(9)
	v_mfma_f32_32x32x16_bf16 v[82:97], v[180:183], v[138:141], v[82:97]
	v_add_f32_e32 v200, v200, v70
	v_exp_f32_e32 v79, v79
	v_add_f32_e32 v201, v201, v71
	v_exp_f32_e32 v80, v80
	v_add_f32_e32 v200, v200, v72
	s_waitcnt lgkmcnt(8)
	v_mfma_f32_32x32x16_bf16 v[98:113], v[184:187], v[138:141], v[98:113]
	ds_read2_b64 v[180:183], v242 offset0:12 offset1:14
	ds_read2_b64 v[184:187], v163 offset0:44 offset1:46
	v_exp_f32_e32 v81, v81
	v_add_f32_e32 v201, v201, v73
	v_cvt_pk_bf16_f32 v228, v74, v75
	v_cvt_pk_bf16_f32 v229, v76, v77
	v_cvt_pk_bf16_f32 v230, v78, v79
	s_waitcnt lgkmcnt(3)
	v_mfma_f32_32x32x16_bf16 v[18:33], v[172:175], v[224:227], v[18:33]
	v_cvt_pk_bf16_f32 v231, v80, v81
	v_add_f32_e32 v200, v200, v74
	v_add_f32_e32 v201, v201, v75
	v_add_f32_e32 v200, v200, v76
	v_add_f32_e32 v201, v201, v77
	v_add_f32_e32 v200, v200, v78
	v_add_f32_e32 v201, v201, v79
	v_add_f32_e32 v200, v200, v80
	s_waitcnt lgkmcnt(2)
	v_mfma_f32_32x32x16_bf16 v[34:49], v[176:179], v[224:227], v[34:49]
	v_add_f32_e32 v201, v201, v81
	v_add_f32_e32 v200, v200, v201
	v_add_f32_e32 v162, v162, v200
	s_waitcnt lgkmcnt(9)
	v_mfma_f32_32x32x16_bf16 v[82:97], v[188:191], v[142:145], v[82:97]
	s_waitcnt lgkmcnt(8)
	v_mfma_f32_32x32x16_bf16 v[98:113], v[192:195], v[142:145], v[98:113]
	s_waitcnt lgkmcnt(7)
	v_mfma_f32_32x32x16_bf16 v[82:97], v[196:199], v[146:149], v[82:97]
	s_waitcnt lgkmcnt(6)
	v_mfma_f32_32x32x16_bf16 v[98:113], v[220:223], v[146:149], v[98:113]
	s_waitcnt lgkmcnt(0)
	v_cndmask_b32_e64 v0, 0, 1, s[44:45]
	v_cmp_ne_u32_e64 s[42:43], 1, v0
	s_andn2_b64 vcc, exec, s[44:45]
	s_cbranch_vccnz .Lt1a_mid
	s_and_b32 s44, s53, 2
	s_mulk_i32 s44, 0x3400
	s_add_i32 s62, s44, 0
	v_add_u32_e32 v0, s62, v151
	s_waitcnt vmcnt(0)
	ds_write_b128 v0, v[118:121]
	s_and_saveexec_b64 s[44:45], s[40:41]
	v_add_u32_e32 v0, s62, v159
	ds_write_b128 v0, v[6:9]
	s_or_b64 exec, exec, s[44:45]

.LBB0_556:
	s_add_i32 s61, s25, 1
	s_cmp_lg_u32 s25, 2
	s_cselect_b32 s25, s61, 0
	s_andn2_b64 vcc, exec, s[44:45]
	s_waitcnt lgkmcnt(0)
	s_barrier
	s_cbranch_vccnz .LBB0_572
	s_cmp_ge_u32 s52, s51
	s_cbranch_scc1 .Lh2_skip
	s_andn2_b32 s62, 2, s52
	s_mulk_i32 s62, 0x3400
	v_add_u32_e32 v0, s62, v160
	s_mul_i32 s62, s25, 0x2200
	v_add_u32_e32 v242, s62, v161
	v_add_u32_e32 v163, 0xe000, v242
	v_add_u32_e32 v242, 0xd000, v242
	ds_read_b128 v[50:53], v0 offset:0
	ds_read_b128 v[66:69], v0 offset:6656
	ds_read_b128 v[164:167], v0 offset:32
	ds_read_b128 v[168:171], v0 offset:6688
	ds_read2_b64 v[238:241], v242 offset0:0 offset1:2
	ds_read2_b64 v[234:237], v163 offset0:32 offset1:34
	ds_read_b128 v[172:175], v0 offset:64
	ds_read_b128 v[176:179], v0 offset:6720
	ds_read_b128 v[180:183], v0 offset:96
	ds_read_b128 v[184:187], v0 offset:6752
	ds_read_b128 v[188:191], v0 offset:128
	ds_read_b128 v[192:195], v0 offset:6784
	ds_read_b128 v[196:199], v0 offset:160
	ds_read_b128 v[220:223], v0 offset:6816
	v_exp_f32_e32 v82, v82
	v_exp_f32_e32 v83, v83
	v_exp_f32_e32 v84, v84
	v_exp_f32_e32 v85, v85
	v_exp_f32_e32 v86, v86
	v_exp_f32_e32 v87, v87
	v_exp_f32_e32 v88, v88
	v_exp_f32_e32 v89, v89
	s_waitcnt lgkmcnt(13)
	v_mfma_f32_32x32x16_bf16 v[50:65], v[50:53], v[122:125], 0
	v_cvt_pk_bf16_f32 v224, v82, v83
	v_cvt_pk_bf16_f32 v225, v84, v85
	v_cvt_pk_bf16_f32 v226, v86, v87
	v_cvt_pk_bf16_f32 v227, v88, v89
	v_exp_f32_e32 v90, v90
	v_add_f32_e32 v200, v82, v83
	s_waitcnt lgkmcnt(12)
	v_mfma_f32_32x32x16_bf16 v[66:81], v[66:69], v[122:125], 0
	v_exp_f32_e32 v91, v91
	v_exp_f32_e32 v92, v92
	v_add_f32_e32 v201, v84, v85
	v_exp_f32_e32 v93, v93
	s_waitcnt lgkmcnt(11)
	v_mfma_f32_32x32x16_bf16 v[50:65], v[164:167], v[126:129], v[50:65]
	v_exp_f32_e32 v94, v94
	v_add_f32_e32 v200, v200, v86
	v_exp_f32_e32 v95, v95
	v_add_f32_e32 v201, v201, v87
	v_exp_f32_e32 v96, v96
	s_waitcnt lgkmcnt(10)
	v_mfma_f32_32x32x16_bf16 v[66:81], v[168:171], v[126:129], v[66:81]
	ds_read2_b64 v[164:167], v242 offset0:4 offset1:6
	ds_read2_b64 v[168:171], v163 offset0:36 offset1:38
	v_add_f32_e32 v200, v200, v88
	v_exp_f32_e32 v97, v97
	v_add_f32_e32 v201, v201, v89
	v_cvt_pk_bf16_f32 v228, v90, v91
	v_cvt_pk_bf16_f32 v229, v92, v93
	s_waitcnt lgkmcnt(11)
	v_mfma_f32_32x32x16_bf16 v[18:33], v[238:241], v[224:227], v[18:33]
	v_cvt_pk_bf16_f32 v230, v94, v95
	v_cvt_pk_bf16_f32 v231, v96, v97
	v_exp_f32_e32 v98, v98
	v_add_f32_e32 v200, v200, v90
	v_exp_f32_e32 v99, v99
	v_add_f32_e32 v201, v201, v91
	s_waitcnt lgkmcnt(10)
	v_mfma_f32_32x32x16_bf16 v[34:49], v[234:237], v[224:227], v[34:49]
	v_exp_f32_e32 v100, v100
	v_add_f32_e32 v200, v200, v92
	v_exp_f32_e32 v101, v101
	v_add_f32_e32 v201, v201, v93
	v_exp_f32_e32 v102, v102
	s_cmp_ge_u32 s52, s5
	s_cbranch_scc1 .Lp2a_561
	s_waitcnt vmcnt(0)
	v_lshl_add_u64 v[118:119], s[54:55], 0, v[154:155]
	v_add_co_u32_e32 v118, vcc, 0xbe0c000, v118
	s_nop 1
	v_addc_co_u32_e32 v119, vcc, 0, v119, vcc
	global_load_dwordx4 v[118:121], v[118:119], off
	s_and_saveexec_b64 s[44:45], s[40:41]
	s_cbranch_execz .Lp2a_560
	v_lshl_add_u64 v[6:7], s[54:55], 0, v[152:153]
	v_add_co_u32_e32 v6, vcc, 0xbe0c000, v6
	s_nop 1
	v_addc_co_u32_e32 v7, vcc, 0, v7, vcc
	global_load_dwordx4 v[6:9], v[6:7], off

.Lp2a_end:
	s_waitcnt lgkmcnt(9)
	v_mfma_f32_32x32x16_bf16 v[50:65], v[172:175], v[134:137], v[50:65]
	v_add_f32_e32 v200, v200, v94
	v_exp_f32_e32 v103, v103
	v_add_f32_e32 v201, v201, v95
	v_exp_f32_e32 v104, v104
	v_add_f32_e32 v200, v200, v96
	s_waitcnt lgkmcnt(8)
	v_mfma_f32_32x32x16_bf16 v[66:81], v[176:179], v[134:137], v[66:81]
	ds_read2_b64 v[172:175], v242 offset0:8 offset1:10
	ds_read2_b64 v[176:179], v163 offset0:40 offset1:42
	v_exp_f32_e32 v105, v105
	v_add_f32_e32 v201, v201, v97
	v_cvt_pk_bf16_f32 v224, v98, v99
	v_cvt_pk_bf16_f32 v225, v100, v101
	v_cvt_pk_bf16_f32 v226, v102, v103
	s_waitcnt lgkmcnt(3)
	v_mfma_f32_32x32x16_bf16 v[18:33], v[164:167], v[228:231], v[18:33]
	v_cvt_pk_bf16_f32 v227, v104, v105
	v_exp_f32_e32 v106, v106
	v_add_f32_e32 v200, v200, v98
	v_exp_f32_e32 v107, v107
	v_add_f32_e32 v201, v201, v99
	s_waitcnt lgkmcnt(2)
	v_mfma_f32_32x32x16_bf16 v[34:49], v[168:171], v[228:231], v[34:49]
	v_exp_f32_e32 v108, v108
	v_add_f32_e32 v200, v200, v100
	v_exp_f32_e32 v109, v109
	v_add_f32_e32 v201, v201, v101
	v_exp_f32_e32 v110, v110
	s_waitcnt lgkmcnt(9)
	v_mfma_f32_32x32x16_bf16 v[50:65], v[180:183], v[138:141], v[50:65]
	v_add_f32_e32 v200, v200, v102
	v_exp_f32_e32 v111, v111
	v_add_f32_e32 v201, v201, v103
	v_exp_f32_e32 v112, v112
	v_add_f32_e32 v200, v200, v104
	s_waitcnt lgkmcnt(8)
	v_mfma_f32_32x32x16_bf16 v[66:81], v[184:187], v[138:141], v[66:81]
	ds_read2_b64 v[180:183], v242 offset0:12 offset1:14
	ds_read2_b64 v[184:187], v163 offset0:44 offset1:46
	v_exp_f32_e32 v113, v113
	v_add_f32_e32 v201, v201, v105
	v_cvt_pk_bf16_f32 v228, v106, v107
	v_cvt_pk_bf16_f32 v229, v108, v109
	v_cvt_pk_bf16_f32 v230, v110, v111
	s_waitcnt lgkmcnt(3)
	v_mfma_f32_32x32x16_bf16 v[18:33], v[172:175], v[224:227], v[18:33]
	v_cvt_pk_bf16_f32 v231, v112, v113
	v_add_f32_e32 v200, v200, v106
	v_add_f32_e32 v201, v201, v107
	v_add_f32_e32 v200, v200, v108
	v_add_f32_e32 v201, v201, v109
	v_add_f32_e32 v200, v200, v110
	v_add_f32_e32 v201, v201, v111
	v_add_f32_e32 v200, v200, v112
	s_waitcnt lgkmcnt(2)
	v_mfma_f32_32x32x16_bf16 v[34:49], v[176:179], v[224:227], v[34:49]
	v_add_f32_e32 v201, v201, v113
	v_add_f32_e32 v200, v200, v201
	v_add_f32_e32 v162, v162, v200
	s_waitcnt lgkmcnt(9)
	v_mfma_f32_32x32x16_bf16 v[50:65], v[188:191], v[142:145], v[50:65]
	s_waitcnt lgkmcnt(8)
	v_mfma_f32_32x32x16_bf16 v[66:81], v[192:195], v[142:145], v[66:81]
	s_waitcnt lgkmcnt(7)
	v_mfma_f32_32x32x16_bf16 v[50:65], v[196:199], v[146:149], v[50:65]
	s_waitcnt lgkmcnt(6)
	v_mfma_f32_32x32x16_bf16 v[66:81], v[220:223], v[146:149], v[66:81]
	s_waitcnt lgkmcnt(0)
	s_mul_i32 s58, s25, 0x2200
	s_and_b64 vcc, exec, s[44:45]
	s_cbranch_vccnz .Lt2a_mid
	s_and_b32 s44, s60, 3
	s_mulk_i32 s44, 0x3400
	s_add_i32 s52, s44, 0
	v_add_u32_e32 v0, s52, v151
	s_waitcnt vmcnt(0)
	ds_write_b128 v0, v[2:5]
	s_and_saveexec_b64 s[44:45], s[40:41]
	v_add_u32_e32 v0, s52, v159
	ds_write_b128 v0, v[10:13]
	s_or_b64 exec, exec, s[44:45]
